# phase 0 weight copies: each matrix's items start where the previous matrix ended (mod the virtual wave count) instead of all at wave 0 - at most 3 items per wave instead of 5 on the lowest blocks
# speedup vs baseline: 1.0285x; 1.0081x over previous
; #define LAS __attribute__((address_space(3)))
; #define KIN(i) (((const float* const __attribute__((address_space(4)))*)kp)[i])
; DEV void tr_matrix(const float* W, int ldw, int K, int Ndst, bf16_t* WT, int map, int nvalid, int src_off, LAS float* scr, int gw, int NGW, int lane) {
;     const int nblk = Ndst / 32, nit = (K / 64) * nblk;
;     for (int it = gw; it < nit; it += NGW) { const int kb = it / nblk, nb = it % nblk, d0 = nb * 32; int s0 = d0;
; template <int LO, int HI>
; DEV void run_phases(LAS unsigned char* lds, const int ph_lo, const int ph_hi, const int G, const int wave0, unsigned& nbar) {
;     ...
;                 for (int rep = 0; rep < nrep0; ++rep) { const int vgw = bal0 ? (bid < 192 ? gw : 1536 + (bid - 192) * 16 + rep * 8 + wave) : gw;
;                     tr_matrix(KIN(I_FHIN), 2048, 1024, 1536, BF(W_W1T) + (size_t)1024 * 1024, 0, 0, 512, scr, vgw, vNGW0, lane);
;                     tr_matrix(KIN(I_FHOUT), 1024, 1024, 1024, BF(W_WOUT), 0, 0, 0, scr, vgw, vNGW0, lane);
;                     tr_matrix(KIN(I_FUP), 2 * DFF, 1024, 2 * DFF, BF(W_WUP), 1, 0, 0, scr, vgw, vNGW0, lane);
;                     tr_matrix(KIN(I_FDOWN), 1024, DFF, 1024, BF(W_WDOWN), 0, 0, 0, scr, vgw, vNGW0, lane); }
.LBB0_41:
	s_sub_i32 s10, s21, 0x300
	s_add_i32 s2, s10, 0xa00
	s_cmp_lt_i32 s10, 0
	s_cselect_b32 s10, s2, s10
	s_cmpk_gt_i32 s10, 0x1ff
	s_cbranch_scc1 .LBB0_62
	s_load_dwordx2 s[2:3], s[14:15], 0x68
	s_waitcnt lgkmcnt(0)
	v_lshl_add_u64 v[14:15], s[2:3], 0, v[2:3]
	s_branch .LBB0_44

; #define LAS __attribute__((address_space(3)))
; #define KIN(i) (((const float* const __attribute__((address_space(4)))*)kp)[i])
; DEV void tr_matrix(const float* W, int ldw, int K, int Ndst, bf16_t* WT, int map, int nvalid, int src_off, LAS float* scr, int gw, int NGW, int lane) {
;     const int nblk = Ndst / 32, nit = (K / 64) * nblk;
;     for (int it = gw; it < nit; it += NGW) { const int kb = it / nblk, nb = it % nblk, d0 = nb * 32; int s0 = d0;
; template <int LO, int HI>
; DEV void run_phases(LAS unsigned char* lds, const int ph_lo, const int ph_hi, const int G, const int wave0, unsigned& nbar) {
;     ...
;                 for (int rep = 0; rep < nrep0; ++rep) { const int vgw = bal0 ? (bid < 192 ? gw : 1536 + (bid - 192) * 16 + rep * 8 + wave) : gw;
;                     tr_matrix(KIN(I_FHIN), 2048, 1024, 1536, BF(W_W1T) + (size_t)1024 * 1024, 0, 0, 512, scr, vgw, vNGW0, lane);
;                     tr_matrix(KIN(I_FHOUT), 1024, 1024, 1024, BF(W_WOUT), 0, 0, 0, scr, vgw, vNGW0, lane);
;                     tr_matrix(KIN(I_FUP), 2 * DFF, 1024, 2 * DFF, BF(W_WUP), 1, 0, 0, scr, vgw, vNGW0, lane);
;                     tr_matrix(KIN(I_FDOWN), 1024, DFF, 1024, BF(W_WDOWN), 0, 0, 0, scr, vgw, vNGW0, lane); }
.LBB0_62:
	s_sub_i32 s22, s21, 0x500
	s_add_i32 s2, s22, 0xa00
	s_cmp_lt_i32 s22, 0
	s_cselect_b32 s22, s2, s22
	s_cmpk_gt_i32 s22, 0xaff
	s_cbranch_scc1 .LBB0_83
	s_load_dwordx2 s[2:3], s[14:15], 0x40
	s_waitcnt lgkmcnt(0)
	v_lshl_add_u64 v[14:15], s[2:3], 0, v[12:13]
	s_branch .LBB0_65

; #define LAS __attribute__((address_space(3)))
; #define KIN(i) (((const float* const __attribute__((address_space(4)))*)kp)[i])
; DEV void tr_matrix(const float* W, int ldw, int K, int Ndst, bf16_t* WT, int map, int nvalid, int src_off, LAS float* scr, int gw, int NGW, int lane) {
;     const int nblk = Ndst / 32, nit = (K / 64) * nblk;
;     for (int it = gw; it < nit; it += NGW) { const int kb = it / nblk, nb = it % nblk, d0 = nb * 32; int s0 = d0;
; template <int LO, int HI>
; DEV void run_phases(LAS unsigned char* lds, const int ph_lo, const int ph_hi, const int G, const int wave0, unsigned& nbar) {
;     ...
;                 for (int rep = 0; rep < nrep0; ++rep) { const int vgw = bal0 ? (bid < 192 ? gw : 1536 + (bid - 192) * 16 + rep * 8 + wave) : gw;
;                     tr_matrix(KIN(I_FHIN), 2048, 1024, 1536, BF(W_W1T) + (size_t)1024 * 1024, 0, 0, 512, scr, vgw, vNGW0, lane);
;                     tr_matrix(KIN(I_FHOUT), 1024, 1024, 1024, BF(W_WOUT), 0, 0, 0, scr, vgw, vNGW0, lane);
;                     tr_matrix(KIN(I_FUP), 2 * DFF, 1024, 2 * DFF, BF(W_WUP), 1, 0, 0, scr, vgw, vNGW0, lane);
;                     tr_matrix(KIN(I_FDOWN), 1024, DFF, 1024, BF(W_WDOWN), 0, 0, 0, scr, vgw, vNGW0, lane); }
.LBB0_83:
	s_sub_i32 s21, s21, 0x600
	s_add_i32 s2, s21, 0xa00
	s_cmp_lt_i32 s21, 0
	s_cselect_b32 s21, s2, s21
	s_cmpk_gt_i32 s21, 0x57f
	s_cbranch_scc1 .LBB0_19
	s_load_dwordx2 s[2:3], s[14:15], 0x58
	s_waitcnt lgkmcnt(0)
	v_lshl_add_u64 v[14:15], s[2:3], 0, v[2:3]
	s_branch .LBB0_86
